# static priority raise for the other wave half: s_setprio 1 once at kernel entry for waves 0-3 of every workgroup
# baseline (speedup 1.0000x reference)
; __global__ void __launch_bounds__(NTHREADS) mega_kernel(Params p) {
;   extern __shared__ __attribute__((aligned(16))) char lds[];
;   cg::grid_group grid = cg::this_grid();
;   unsigned bar_gen = 0;
;   for (int ph = 0; ph < NPHASE; ++ph) {
;     ...
;     const int nrep = (REPQ >= 100) ? ((ph == REPQ - 100) ? 2 : 1) : ((ph > 0 && ph < NPHASE - 1 && (ph - 1) % 14 == REPQ) ? 2 : 1);
;     ...
;     const int nrep = 1;
;     ...
;     if (ph == NPHASE - 2) continue;
;     for (int rep = 0; rep < nrep; ++rep) {
;       run_phase(p, ph, lds, rep);
_Z11mega_kernel6Params:
	s_load_dword s33, s[0:1], 0xc8
	s_add_u32 s8, s0, 0xc8
	s_load_dwordx2 s[34:35], s[0:1], 0xc0
	s_addc_u32 s9, s1, 0
	s_lshl_b32 s3, s2, 3
	s_waitcnt lgkmcnt(0)
	s_lshl_b32 s10, s33, 3
	s_cmp_eq_u32 s2, 0
	v_writelane_b32 v253, s3, 0
	s_cselect_b64 s[4:5], -1, 0
	v_writelane_b32 v253, s4, 1
	v_and_b32_e32 v129, 0x3ff, v0
	v_and_b32_e32 v1, 32, v0
	v_writelane_b32 v253, s5, 2
	s_load_dwordx4 s[4:7], s[0:1], 0xb0
	s_add_u32 s12, s34, 0x65c0000
	s_addc_u32 s13, s35, 0
	v_writelane_b32 v253, s12, 3
	v_and_b32_e32 v0, 0x3fffffff, v0
	s_load_dwordx8 s[40:47], s[0:1], 0x90
	v_writelane_b32 v253, s13, 4
	s_add_u32 s12, s34, 0x65c1800
	s_addc_u32 s13, s35, 0
	v_writelane_b32 v253, s12, 5
	s_cmp_lt_i32 s2, 4
	v_mbcnt_lo_u32_b32 v2, -1, 0
	v_writelane_b32 v253, s13, 6
	s_cselect_b64 s[12:13], -1, 0
	v_writelane_b32 v253, s12, 7
	v_mbcnt_hi_u32_b32 v188, -1, v2
	v_and_b32_e32 v2, 64, v188
	v_writelane_b32 v253, s13, 8
	s_add_u32 s12, s34, 0x65c0100
	s_addc_u32 s13, s35, 0
	v_writelane_b32 v253, s12, 9
	s_cmpk_lt_i32 s2, 0x32e0
	v_mov_b32_e32 v128, 0x358637bd
	v_writelane_b32 v253, s13, 10
	s_cselect_b64 s[12:13], -1, 0
	s_add_u32 s88, s34, 0x65c2000
	v_writelane_b32 v253, s12, 11
	s_addc_u32 s89, s35, 0
	v_mov_b32_e32 v131, 0
	v_writelane_b32 v253, s13, 12
	s_add_u32 s12, s34, 0xa5c2000
	s_addc_u32 s13, s35, 0
	v_writelane_b32 v253, s12, 13
	s_cmpk_lt_i32 s2, 0x400
	v_add_u32_e32 v189, 64, v2
	v_writelane_b32 v253, s13, 14
	s_cselect_b64 s[12:13], -1, 0
	v_writelane_b32 v253, s12, 15
	s_cmpk_lt_i32 s2, 0x1600
	v_xor_b32_e32 v190, 32, v188
	v_writelane_b32 v253, s13, 16
	s_cselect_b64 s[12:13], -1, 0
	v_writelane_b32 v253, s12, 17
	v_xor_b32_e32 v191, 16, v188
	v_xor_b32_e32 v192, 8, v188
	v_writelane_b32 v253, s13, 18
	s_add_u32 s12, s34, 0x18594000
	s_addc_u32 s13, s35, 0
	v_writelane_b32 v253, s12, 19
	v_xor_b32_e32 v193, 4, v188
	v_xor_b32_e32 v194, 2, v188
	v_writelane_b32 v253, s13, 20
	s_add_u32 s12, s34, 0x16d14000
	s_addc_u32 s13, s35, 0
	v_writelane_b32 v253, s12, 21
	v_xor_b32_e32 v195, 1, v188
	v_mov_b32_e32 v196, 0x80
	v_writelane_b32 v253, s13, 22
	s_add_u32 s12, s34, 0x16d94000
	s_addc_u32 s13, s35, 0
	v_writelane_b32 v253, s12, 23
	v_mov_b32_e32 v197, 0x1000
	v_mov_b32_e32 v198, 0x800
	v_writelane_b32 v253, s13, 24
	s_add_u32 s12, s34, 0xf5c4000
	s_addc_u32 s13, s35, 0
	v_writelane_b32 v253, s12, 25
	v_mov_b32_e32 v199, 0xff800000
	v_mov_b32_e32 v200, 31
	v_writelane_b32 v253, s13, 26
	s_add_u32 s12, s34, 0xfdc4000
	s_addc_u32 s13, s35, 0
	v_writelane_b32 v253, s12, 27
	v_mov_b32_e32 v201, 6
	v_mov_b32_e32 v202, 7
	v_writelane_b32 v253, s13, 28
	s_add_u32 s12, s34, 0x165c4008
	s_addc_u32 s13, s35, 0
	v_writelane_b32 v253, s12, 29
	v_mov_b32_e32 v203, 3
	v_mov_b32_e32 v204, 2
	v_writelane_b32 v253, s13, 30
	s_add_u32 s12, s34, 0x105c4000
	s_addc_u32 s13, s35, 0
	v_writelane_b32 v253, s12, 31
	v_mov_b32_e32 v205, 0x80000
	v_mov_b32_e32 v206, 15
	v_writelane_b32 v253, s13, 32
	s_add_u32 s12, s34, 0x10dc4000
	s_addc_u32 s13, s35, 0
	v_writelane_b32 v253, s12, 33
	v_mov_b32_e32 v207, 5
	v_mov_b32_e32 v208, 0xfc1
	v_writelane_b32 v253, s13, 34
	s_add_u32 s12, s34, 0x16c84000
	s_addc_u32 s13, s35, 0
	v_writelane_b32 v253, s12, 35
	v_mov_b32_e32 v209, 12
	v_mov_b32_e32 v210, 0xfffff880
	v_writelane_b32 v253, s13, 36
	s_add_u32 s12, s34, 0x16c04000
	s_addc_u32 s13, s35, 0
	v_writelane_b32 v253, s12, 37
	v_mov_b32_e32 v211, 0xfffffb80
	v_mov_b32_e32 v212, 0x10dc4000
	v_writelane_b32 v253, s13, 38
	s_add_u32 s12, s34, 0x165c4000
	s_addc_u32 s13, s35, 0
	v_writelane_b32 v253, s12, 39
	v_mov_b32_e32 v213, 0x105c4000
	v_mov_b32_e32 v214, 0x280
	v_writelane_b32 v253, s13, 40
	s_add_u32 s12, s34, 0x16804000
	s_addc_u32 s13, s35, 0
	v_writelane_b32 v253, s12, 41
	s_cmp_lt_i32 s2, 64
	v_mov_b32_e32 v215, 0x300
	v_writelane_b32 v253, s13, 42
	s_cselect_b64 s[12:13], -1, 0
	v_writelane_b32 v253, s12, 43
	v_mov_b32_e32 v216, 0x380
	s_mov_b32 s53, 0x8000
	v_writelane_b32 v253, s13, 44
	s_add_u32 s12, s34, 0xbdc2000
	s_addc_u32 s13, s35, 0
	v_writelane_b32 v253, s12, 45
	s_movk_i32 s84, 0x801
	s_movk_i32 s85, 0x200
	v_writelane_b32 v253, s13, 46
	s_add_u32 s12, s34, 0x16d04000
	s_addc_u32 s13, s35, 0
	v_writelane_b32 v253, s12, 47
	s_mov_b64 s[80:81], 0x1000
	s_mov_b32 s30, 0x3a800000
	v_writelane_b32 v253, s13, 48
	s_add_u32 s12, s34, 0x115c4000
	s_addc_u32 s13, s35, 0
	v_writelane_b32 v253, s12, 49
	s_mov_b64 s[92:93], 0x80
	s_mov_b64 s[74:75], 0xa5c2180
	v_writelane_b32 v253, s13, 50
	s_add_u32 s12, s34, 0x125c4000
	s_addc_u32 s13, s35, 0
	v_writelane_b32 v253, s12, 51
	s_add_u32 s3, s34, 0xe5c2000
	s_mov_b64 s[78:79], 0x100
	v_writelane_b32 v253, s13, 52
	v_writelane_b32 v253, s3, 53
	s_addc_u32 s3, s35, 0
	s_cmpk_lt_i32 s2, 0x80
	v_writelane_b32 v253, s3, 54
	s_cselect_b64 s[12:13], -1, 0
	v_writelane_b32 v253, s12, 55
	s_add_u32 s3, s34, 0x65c0040
	s_mov_b64 s[72:73], 0x180
	v_writelane_b32 v253, s13, 56
	v_writelane_b32 v253, s3, 57
	s_addc_u32 s3, s35, 0
	s_add_u32 s12, s34, 0xcdc2000
	v_writelane_b32 v253, s3, 58
	s_addc_u32 s13, s35, 0
	v_writelane_b32 v253, s12, 59
	s_mov_b64 s[28:29], 0x280
	s_mov_b64 s[76:77], 0x300
	v_writelane_b32 v253, s13, 60
	s_add_u32 s12, s34, 0x135c4000
	s_addc_u32 s13, s35, 0
	v_writelane_b32 v253, s12, 61
	s_mov_b64 s[82:83], 0x680
	s_mov_b64 s[94:95], 0x700
	v_writelane_b32 v253, s13, 62
	s_add_u32 s12, s34, 0x14dc4000
	s_addc_u32 s13, s35, 0
	v_writelane_b32 v253, s12, 63
	s_cmpk_lt_i32 s2, 0xc80
	s_mov_b64 s[90:91], 0x780
	v_writelane_b32 v254, s13, 0
	s_load_dwordx16 s[12:27], s[0:1], 0x0
	v_writelane_b32 v254, s2, 1
	s_cselect_b64 s[2:3], -1, 0
	v_writelane_b32 v254, s2, 2
	s_mov_b64 s[96:97], 0x65c2100
	s_mov_b64 s[86:87], 0x2740100
	v_writelane_b32 v254, s3, 3
	s_waitcnt lgkmcnt(0)
; __global__ void __launch_bounds__(NTHREADS) mega_kernel(Params p) {
;   extern __shared__ __attribute__((aligned(16))) char lds[];
;   cg::grid_group grid = cg::this_grid();
;   unsigned bar_gen = 0;
;   for (int ph = 0; ph < NPHASE; ++ph) {
;     ...
;     const int nrep = (REPQ >= 100) ? ((ph == REPQ - 100) ? 2 : 1) : ((ph > 0 && ph < NPHASE - 1 && (ph - 1) % 14 == REPQ) ? 2 : 1);
;     ...
;     const int nrep = 1;
;     ...
;     if (ph == NPHASE - 2) continue;
;     for (int rep = 0; rep < nrep; ++rep) {
;       run_phase(p, ph, lds, rep);
	s_add_u32 s2, s16, 0x1000
	v_writelane_b32 v254, s12, 4
	s_addc_u32 s3, s17, 0
	s_mov_b32 s52, 0
	v_writelane_b32 v254, s13, 5
	v_writelane_b32 v254, s14, 6
	v_writelane_b32 v254, s15, 7
	v_writelane_b32 v254, s16, 8
	v_writelane_b32 v254, s17, 9
	v_writelane_b32 v254, s18, 10
	v_writelane_b32 v254, s19, 11
	v_writelane_b32 v254, s20, 12
	v_writelane_b32 v254, s21, 13
	v_writelane_b32 v254, s22, 14
	v_writelane_b32 v254, s23, 15
	v_writelane_b32 v254, s24, 16
	v_writelane_b32 v254, s25, 17
	v_writelane_b32 v254, s26, 18
	v_writelane_b32 v254, s27, 19
	v_writelane_b32 v254, s2, 20
	s_movk_i32 s20, 0x201
	s_mov_b32 s21, 0
	v_writelane_b32 v254, s3, 21
	s_add_u32 s2, s34, 0x16a04000
	s_addc_u32 s3, s35, 0
	v_writelane_b32 v254, s2, 22
	v_cmp_eq_u32_e64 s[12:13], 0, v1
	s_mov_b64 s[16:17], 0x65c2180
	v_writelane_b32 v254, s3, 23
	s_add_u32 s2, s34, 0xedc3000
	v_writelane_b32 v254, s2, 24
	s_addc_u32 s2, s35, 0
	v_writelane_b32 v254, s2, 25
	s_add_u32 s2, s6, 0xc00
	v_writelane_b32 v254, s4, 26
	s_addc_u32 s3, s7, 0
	s_ashr_i32 s11, s10, 31
	v_writelane_b32 v254, s5, 27
	v_writelane_b32 v254, s6, 28
	v_writelane_b32 v254, s7, 29
	v_writelane_b32 v254, s2, 30
	s_lshl_b64 s[36:37], s[10:11], 12
	v_writelane_b32 v252, s10, 0
	v_writelane_b32 v254, s3, 31
	s_add_i32 s2, 0, 0x1000
	v_writelane_b32 v254, s2, 32
	s_mov_b32 s2, 0
	v_writelane_b32 v254, s2, 33
	v_cmp_eq_u32_e64 s[2:3], 0, v0
	v_writelane_b32 v252, s11, 1
	s_movk_i32 s6, 0x1600
	v_writelane_b32 v254, s2, 34
	s_mov_b32 s5, 0xff800000
	s_movk_i32 s7, 0x81
	v_writelane_b32 v254, s3, 35
	v_cmp_eq_u32_e64 s[2:3], 0, v129
	s_mov_b64 s[18:19], 0x2740180
	v_writelane_b32 v252, s36, 2
	v_writelane_b32 v254, s2, 36
	s_nop 0
	v_writelane_b32 v252, s37, 3
	v_writelane_b32 v254, s3, 37
	v_writelane_b32 v254, s40, 38
	s_mov_b64 s[2:3], 0xa5c2100
	s_nop 0
	v_writelane_b32 v254, s41, 39
	v_writelane_b32 v254, s42, 40
	v_writelane_b32 v254, s43, 41
	v_writelane_b32 v254, s44, 42
	v_writelane_b32 v254, s45, 43
	v_writelane_b32 v254, s46, 44
	v_writelane_b32 v254, s47, 45
	v_writelane_b32 v254, s0, 46
	s_load_dwordx16 s[56:71], s[0:1], 0x50
	s_nop 0
	v_writelane_b32 v254, s1, 47
	s_mov_b64 s[0:1], s[8:9]
	s_waitcnt lgkmcnt(0)
	v_writelane_b32 v254, s56, 48
	s_nop 1
	v_writelane_b32 v254, s57, 49
	v_writelane_b32 v254, s58, 50
	v_writelane_b32 v254, s59, 51
	v_writelane_b32 v254, s60, 52
	v_writelane_b32 v254, s61, 53
	v_writelane_b32 v254, s62, 54
	v_writelane_b32 v254, s63, 55
	v_writelane_b32 v254, s64, 56
	v_writelane_b32 v254, s65, 57
	v_writelane_b32 v254, s66, 58
	v_writelane_b32 v254, s67, 59
	v_writelane_b32 v254, s68, 60
	v_writelane_b32 v254, s69, 61
	v_writelane_b32 v254, s70, 62
	v_writelane_b32 v254, s71, 63
	v_cmp_lt_u32_e32 vcc, 0xff, v129
	s_cbranch_vccnz .Lprio_skip
	s_setprio 1
